# attention A tile loop: next tile's K/V loads issued at the start of each half-step (before QK^T) instead of mid-step
# baseline (speedup 1.0000x reference)
.LBB0_986:
	s_sub_i32 s33, s39, 64
	s_mul_hi_u32 s43, s33, s3
	s_mul_i32 s42, s33, s3
	s_lshl_b64 s[42:43], s[42:43], 1
	s_add_u32 s4, s48, s42
	s_addc_u32 s5, s49, s43
	v_lshl_add_u64 v[18:19], s[4:5], 0, v[212:213]
	v_lshl_add_u64 v[20:21], s[4:5], 0, v[216:217]
	global_load_dwordx4 v[196:199], v[18:19], off
	global_load_dwordx4 v[200:203], v[20:21], off
	s_add_u32 s4, s46, s42
	s_addc_u32 s5, s47, s43
	v_lshl_add_u64 v[18:19], s[4:5], 0, v[212:213]
	v_lshl_add_u64 v[20:21], s[4:5], 0, v[216:217]
	global_load_dwordx4 v[204:207], v[18:19], off
	global_load_dwordx4 v[208:211], v[20:21], off
	s_add_i32 s33, s39, 0xffffff80
	s_cmp_gt_i32 s33, s25
	s_cselect_b64 s[4:5], -1, 0
	s_add_i32 s41, s39, 0xffffffbf
	s_cmp_lt_i32 s41, s28
	s_cselect_b64 s[42:43], -1, 0
	s_or_b64 s[4:5], s[4:5], s[42:43]
	s_and_b64 vcc, exec, s[4:5]
	s_cbranch_vccnz .LBB0_988
	v_add_u32_e32 v17, v225, v224
	ds_read_b128 v[18:21], v17 offset:49152
	v_add_u32_e32 v22, v226, v224
	v_add_u32_e32 v23, v227, v224
	v_add_u32_e32 v24, v228, v224
	s_waitcnt lgkmcnt(0)
	v_mfma_f32_32x32x16_bf16 v[96:111], v[18:21], v[176:179], 0
	ds_read_b128 v[18:21], v17 offset:57344
	s_waitcnt lgkmcnt(0)
	v_mfma_f32_32x32x16_bf16 v[112:127], v[18:21], v[176:179], 0
	ds_read_b128 v[18:21], v22 offset:49152
	s_waitcnt lgkmcnt(0)
	v_mfma_f32_32x32x16_bf16 v[96:111], v[18:21], v[172:175], v[96:111]
	ds_read_b128 v[18:21], v22 offset:57344
	s_waitcnt lgkmcnt(0)
	v_mfma_f32_32x32x16_bf16 v[112:127], v[18:21], v[172:175], v[112:127]
	ds_read_b128 v[18:21], v23 offset:49152
	s_waitcnt lgkmcnt(0)
	v_mfma_f32_32x32x16_bf16 v[96:111], v[18:21], v[168:171], v[96:111]
	ds_read_b128 v[18:21], v23 offset:57344
	s_waitcnt lgkmcnt(0)
	v_mfma_f32_32x32x16_bf16 v[112:127], v[18:21], v[168:171], v[112:127]
	ds_read_b128 v[18:21], v24 offset:49152
	s_waitcnt lgkmcnt(0)
	v_mfma_f32_32x32x16_bf16 v[96:111], v[18:21], v[164:167], v[96:111]
	ds_read_b128 v[18:21], v24 offset:57344
	s_waitcnt lgkmcnt(0)
	v_mfma_f32_32x32x16_bf16 v[112:127], v[18:21], v[164:167], v[112:127]
	ds_read_b128 v[18:21], v17 offset:49280
	s_waitcnt lgkmcnt(0)
	v_mfma_f32_32x32x16_bf16 v[96:111], v[18:21], v[160:163], v[96:111]
	ds_read_b128 v[18:21], v17 offset:57472
	s_waitcnt lgkmcnt(0)
	v_mfma_f32_32x32x16_bf16 v[112:127], v[18:21], v[160:163], v[112:127]
	ds_read_b128 v[18:21], v22 offset:49280
	s_waitcnt lgkmcnt(0)
	v_mfma_f32_32x32x16_bf16 v[96:111], v[18:21], v[10:13], v[96:111]
	ds_read_b128 v[18:21], v22 offset:57472
	s_waitcnt lgkmcnt(0)
	v_mfma_f32_32x32x16_bf16 v[112:127], v[18:21], v[10:13], v[112:127]
	ds_read_b128 v[18:21], v23 offset:49280
	s_waitcnt lgkmcnt(0)
	v_mfma_f32_32x32x16_bf16 v[96:111], v[18:21], v[6:9], v[96:111]
	ds_read_b128 v[18:21], v23 offset:57472
	s_waitcnt lgkmcnt(0)
	v_mfma_f32_32x32x16_bf16 v[112:127], v[18:21], v[6:9], v[112:127]
	ds_read_b128 v[18:21], v24 offset:49280
	s_waitcnt lgkmcnt(0)
	v_mfma_f32_32x32x16_bf16 v[96:111], v[18:21], v[2:5], v[96:111]
	ds_read_b128 v[18:21], v24 offset:57472
	s_waitcnt lgkmcnt(0)
	v_mfma_f32_32x32x16_bf16 v[112:127], v[18:21], v[2:5], v[112:127]
	s_branch .LBB0_989

.LBB0_991:
	s_xor_b64 s[42:43], s[68:69], -1
	s_sub_i32 s40, s39, 64
	s_andn2_b64 vcc, exec, s[42:43]
	s_cbranch_vccnz .LBB0_993
	ds_read_b64_tr_b16 v[18:19], v223 offset:0
	ds_read_b64_tr_b16 v[20:21], v223 offset:0x800
	ds_read_b64_tr_b16 v[22:23], v223 offset:0x1000
	ds_read_b64_tr_b16 v[24:25], v223 offset:0x1800
	ds_read_b64_tr_b16 v[26:27], v223 offset:0x2000
	ds_read_b64_tr_b16 v[28:29], v223 offset:0x2800
	ds_read_b64_tr_b16 v[128:129], v223 offset:0x3000
	ds_read_b64_tr_b16 v[130:131], v223 offset:0x3800
	s_waitcnt lgkmcnt(0)
	s_nop 0
	v_mfma_f32_32x32x16_bf16 v[64:79], v[180:183], v[18:21], v[64:79]
	ds_read_b64_tr_b16 v[18:19], v223 offset:0x200
	ds_read_b64_tr_b16 v[20:21], v223 offset:0xa00
	v_mfma_f32_32x32x16_bf16 v[64:79], v[184:187], v[22:25], v[64:79]
	ds_read_b64_tr_b16 v[22:23], v223 offset:0x1200
	ds_read_b64_tr_b16 v[24:25], v223 offset:0x1a00
	v_mfma_f32_32x32x16_bf16 v[64:79], v[188:191], v[26:29], v[64:79]
	ds_read_b64_tr_b16 v[26:27], v223 offset:0x2200
	ds_read_b64_tr_b16 v[28:29], v223 offset:0x2a00
	v_mfma_f32_32x32x16_bf16 v[64:79], v[192:195], v[128:131], v[64:79]
	ds_read_b64_tr_b16 v[128:129], v223 offset:0x3200
	ds_read_b64_tr_b16 v[130:131], v223 offset:0x3a00
	s_waitcnt lgkmcnt(0)
	v_mfma_f32_32x32x16_bf16 v[80:95], v[180:183], v[18:21], v[80:95]
	ds_read_b64_tr_b16 v[18:19], v223 offset:0x400
	ds_read_b64_tr_b16 v[20:21], v223 offset:0xc00
	v_mfma_f32_32x32x16_bf16 v[80:95], v[184:187], v[22:25], v[80:95]
	ds_read_b64_tr_b16 v[22:23], v223 offset:0x1400
	ds_read_b64_tr_b16 v[24:25], v223 offset:0x1c00
	v_mfma_f32_32x32x16_bf16 v[80:95], v[188:191], v[26:29], v[80:95]
	ds_read_b64_tr_b16 v[26:27], v223 offset:0x2400
	ds_read_b64_tr_b16 v[28:29], v223 offset:0x2c00
	v_mfma_f32_32x32x16_bf16 v[80:95], v[192:195], v[128:131], v[80:95]
	ds_read_b64_tr_b16 v[128:129], v223 offset:0x3400
	ds_read_b64_tr_b16 v[130:131], v223 offset:0x3c00
	s_waitcnt lgkmcnt(0)
	v_mfma_f32_32x32x16_bf16 v[48:63], v[180:183], v[18:21], v[48:63]
	ds_read_b64_tr_b16 v[18:19], v223 offset:0x600
	ds_read_b64_tr_b16 v[20:21], v223 offset:0xe00
	v_mfma_f32_32x32x16_bf16 v[48:63], v[184:187], v[22:25], v[48:63]
	ds_read_b64_tr_b16 v[22:23], v223 offset:0x1600
	ds_read_b64_tr_b16 v[24:25], v223 offset:0x1e00
	v_mfma_f32_32x32x16_bf16 v[48:63], v[188:191], v[26:29], v[48:63]
	ds_read_b64_tr_b16 v[26:27], v223 offset:0x2600
	ds_read_b64_tr_b16 v[28:29], v223 offset:0x2e00
	v_mfma_f32_32x32x16_bf16 v[48:63], v[192:195], v[128:131], v[48:63]
	ds_read_b64_tr_b16 v[128:129], v223 offset:0x3600
	ds_read_b64_tr_b16 v[130:131], v223 offset:0x3e00
	s_waitcnt lgkmcnt(0)
	v_mfma_f32_32x32x16_bf16 v[32:47], v[180:183], v[18:21], v[32:47]
	v_mfma_f32_32x32x16_bf16 v[32:47], v[184:187], v[22:25], v[32:47]
	v_mfma_f32_32x32x16_bf16 v[32:47], v[188:191], v[26:29], v[32:47]
	v_mfma_f32_32x32x16_bf16 v[32:47], v[192:195], v[128:131], v[32:47]

.LBB0_1001:
	s_waitcnt lgkmcnt(0)
	s_add_i32 s33, s38, 1
	s_cmp_ge_i32 s33, s29
	s_cbranch_scc1 .Lhs2_noload
	s_mul_hi_u32 s43, s39, s3
	s_mul_i32 s42, s39, s3
	s_lshl_b64 s[42:43], s[42:43], 1
	s_add_u32 s44, s46, s42
	s_addc_u32 s45, s47, s43
	s_add_u32 s42, s48, s42
	s_addc_u32 s43, s49, s43
	v_lshl_add_u64 v[18:19], s[42:43], 0, v[212:213]
	v_lshl_add_u64 v[20:21], s[42:43], 0, v[216:217]
	global_load_dwordx4 v[196:199], v[18:19], off
	global_load_dwordx4 v[200:203], v[20:21], off
	v_lshl_add_u64 v[18:19], s[44:45], 0, v[212:213]
	v_lshl_add_u64 v[20:21], s[44:45], 0, v[216:217]
	global_load_dwordx4 v[204:207], v[18:19], off
	global_load_dwordx4 v[208:211], v[20:21], off
.Lhs2_noload:
	s_barrier
	s_cmp_gt_i32 s40, s25
	s_cselect_b64 s[42:43], -1, 0
	s_add_i32 s33, s39, -1
	s_cmp_lt_i32 s33, s28
	s_cselect_b64 s[44:45], -1, 0
	s_or_b64 s[68:69], s[42:43], s[44:45]
	s_and_b64 vcc, exec, s[68:69]
	s_cbranch_vccnz .LBB0_1003
	v_add_u32_e32 v17, v225, v224
	ds_read_b128 v[18:21], v17 offset:32768
	v_add_u32_e32 v22, v226, v224
	v_add_u32_e32 v23, v227, v224
	v_add_u32_e32 v24, v228, v224
	s_waitcnt lgkmcnt(0)
	v_mfma_f32_32x32x16_bf16 v[128:143], v[18:21], v[176:179], 0
	ds_read_b128 v[18:21], v17 offset:40960
	s_waitcnt lgkmcnt(0)
	v_mfma_f32_32x32x16_bf16 v[144:159], v[18:21], v[176:179], 0
	ds_read_b128 v[18:21], v22 offset:32768
	s_waitcnt lgkmcnt(0)
	v_mfma_f32_32x32x16_bf16 v[128:143], v[18:21], v[172:175], v[128:143]
	ds_read_b128 v[18:21], v22 offset:40960
	s_waitcnt lgkmcnt(0)
	v_mfma_f32_32x32x16_bf16 v[144:159], v[18:21], v[172:175], v[144:159]
	ds_read_b128 v[18:21], v23 offset:32768
	s_waitcnt lgkmcnt(0)
	v_mfma_f32_32x32x16_bf16 v[128:143], v[18:21], v[168:171], v[128:143]
	ds_read_b128 v[18:21], v23 offset:40960
	s_waitcnt lgkmcnt(0)
	v_mfma_f32_32x32x16_bf16 v[144:159], v[18:21], v[168:171], v[144:159]
	ds_read_b128 v[18:21], v24 offset:32768
	s_waitcnt lgkmcnt(0)
	v_mfma_f32_32x32x16_bf16 v[128:143], v[18:21], v[164:167], v[128:143]
	ds_read_b128 v[18:21], v24 offset:40960
	s_waitcnt lgkmcnt(0)
	v_mfma_f32_32x32x16_bf16 v[144:159], v[18:21], v[164:167], v[144:159]
	ds_read_b128 v[18:21], v17 offset:32896
	s_waitcnt lgkmcnt(0)
	v_mfma_f32_32x32x16_bf16 v[128:143], v[18:21], v[160:163], v[128:143]
	ds_read_b128 v[18:21], v17 offset:41088
	s_waitcnt lgkmcnt(0)
	v_mfma_f32_32x32x16_bf16 v[144:159], v[18:21], v[160:163], v[144:159]
	ds_read_b128 v[18:21], v22 offset:32896
	s_waitcnt lgkmcnt(0)
	v_mfma_f32_32x32x16_bf16 v[128:143], v[18:21], v[10:13], v[128:143]
	ds_read_b128 v[18:21], v22 offset:41088
	s_waitcnt lgkmcnt(0)
	v_mfma_f32_32x32x16_bf16 v[144:159], v[18:21], v[10:13], v[144:159]
	ds_read_b128 v[18:21], v23 offset:32896
	s_waitcnt lgkmcnt(0)
	v_mfma_f32_32x32x16_bf16 v[128:143], v[18:21], v[6:9], v[128:143]
	ds_read_b128 v[18:21], v23 offset:41088
	s_waitcnt lgkmcnt(0)
	v_mfma_f32_32x32x16_bf16 v[144:159], v[18:21], v[6:9], v[144:159]
	ds_read_b128 v[18:21], v24 offset:32896
	s_waitcnt lgkmcnt(0)
	v_mfma_f32_32x32x16_bf16 v[128:143], v[18:21], v[2:5], v[128:143]
	ds_read_b128 v[18:21], v24 offset:41088
	s_waitcnt lgkmcnt(0)
	v_mfma_f32_32x32x16_bf16 v[144:159], v[18:21], v[2:5], v[144:159]
	s_and_b64 vcc, exec, s[4:5]
	s_cbranch_vccz .LBB0_1004
	s_branch .LBB0_1005

.LBB0_1007:
	s_xor_b64 s[4:5], s[68:69], -1
	s_andn2_b64 vcc, exec, s[4:5]
	v_mov_b32_e32 v245, 1.0
	s_cbranch_vccz .LBB0_1010
	s_branch .LBB0_1013
.LBB0_1008:
	s_and_b64 vcc, exec, s[4:5]
	s_cbranch_vccnz .LBB0_1007
.LBB0_1009:
	ds_read_b64_tr_b16 v[18:19], v223 offset:0x4000
	ds_read_b64_tr_b16 v[20:21], v223 offset:0x4800
	ds_read_b64_tr_b16 v[22:23], v223 offset:0x5000
	ds_read_b64_tr_b16 v[24:25], v223 offset:0x5800
	ds_read_b64_tr_b16 v[26:27], v223 offset:0x6000
	ds_read_b64_tr_b16 v[28:29], v223 offset:0x6800
	ds_read_b64_tr_b16 v[246:247], v223 offset:0x7000
	ds_read_b64_tr_b16 v[248:249], v223 offset:0x7800
	s_waitcnt lgkmcnt(0)
	s_nop 0
	v_mfma_f32_32x32x16_bf16 v[64:79], v[180:183], v[18:21], v[64:79]
	ds_read_b64_tr_b16 v[18:19], v223 offset:0x4200
	ds_read_b64_tr_b16 v[20:21], v223 offset:0x4a00
	v_mfma_f32_32x32x16_bf16 v[64:79], v[184:187], v[22:25], v[64:79]
	ds_read_b64_tr_b16 v[22:23], v223 offset:0x5200
	ds_read_b64_tr_b16 v[24:25], v223 offset:0x5a00
	v_mfma_f32_32x32x16_bf16 v[64:79], v[188:191], v[26:29], v[64:79]
	ds_read_b64_tr_b16 v[26:27], v223 offset:0x6200
	ds_read_b64_tr_b16 v[28:29], v223 offset:0x6a00
	v_mfma_f32_32x32x16_bf16 v[64:79], v[192:195], v[246:249], v[64:79]
	ds_read_b64_tr_b16 v[246:247], v223 offset:0x7200
	ds_read_b64_tr_b16 v[248:249], v223 offset:0x7a00
	s_waitcnt lgkmcnt(0)
	v_mfma_f32_32x32x16_bf16 v[80:95], v[180:183], v[18:21], v[80:95]
	ds_read_b64_tr_b16 v[18:19], v223 offset:0x4400
	ds_read_b64_tr_b16 v[20:21], v223 offset:0x4c00
	v_mfma_f32_32x32x16_bf16 v[80:95], v[184:187], v[22:25], v[80:95]
	ds_read_b64_tr_b16 v[22:23], v223 offset:0x5400
	ds_read_b64_tr_b16 v[24:25], v223 offset:0x5c00
	v_mfma_f32_32x32x16_bf16 v[80:95], v[188:191], v[26:29], v[80:95]
	ds_read_b64_tr_b16 v[26:27], v223 offset:0x6400
	ds_read_b64_tr_b16 v[28:29], v223 offset:0x6c00
	v_mfma_f32_32x32x16_bf16 v[80:95], v[192:195], v[246:249], v[80:95]
	ds_read_b64_tr_b16 v[246:247], v223 offset:0x7400
	ds_read_b64_tr_b16 v[248:249], v223 offset:0x7c00
	s_waitcnt lgkmcnt(0)
	v_mfma_f32_32x32x16_bf16 v[48:63], v[180:183], v[18:21], v[48:63]
	ds_read_b64_tr_b16 v[18:19], v223 offset:0x4600
	ds_read_b64_tr_b16 v[20:21], v223 offset:0x4e00
	v_mfma_f32_32x32x16_bf16 v[48:63], v[184:187], v[22:25], v[48:63]
	ds_read_b64_tr_b16 v[22:23], v223 offset:0x5600
	ds_read_b64_tr_b16 v[24:25], v223 offset:0x5e00
	v_mfma_f32_32x32x16_bf16 v[48:63], v[188:191], v[26:29], v[48:63]
	ds_read_b64_tr_b16 v[26:27], v223 offset:0x6600
	ds_read_b64_tr_b16 v[28:29], v223 offset:0x6e00
	v_mfma_f32_32x32x16_bf16 v[48:63], v[192:195], v[246:249], v[48:63]
	ds_read_b64_tr_b16 v[246:247], v223 offset:0x7600
	ds_read_b64_tr_b16 v[248:249], v223 offset:0x7e00
	s_waitcnt lgkmcnt(0)
	v_mfma_f32_32x32x16_bf16 v[32:47], v[180:183], v[18:21], v[32:47]
	v_mfma_f32_32x32x16_bf16 v[32:47], v[184:187], v[22:25], v[32:47]
	v_mfma_f32_32x32x16_bf16 v[32:47], v[188:191], v[26:29], v[32:47]
	v_mfma_f32_32x32x16_bf16 v[32:47], v[192:195], v[246:249], v[32:47]
	s_xor_b64 s[4:5], s[68:69], -1
	s_andn2_b64 vcc, exec, s[4:5]
	v_mov_b32_e32 v245, 1.0
	s_cbranch_vccnz .LBB0_1013
